# removed the compiler's full vmcnt(0) drains at the Swiglu GEMM prologue exit and at the residual GEMM's per-unit K-loop entry (counted waits already cover what is read); on top of the permlane-swap bu
# baseline (speedup 1.0000x reference)
; #define PG8_STAGE(bufoff, gbase, voff) do { _Pragma("unroll") for (int _i = 0; _i < 2; ++_i) \
;         __builtin_amdgcn_global_load_lds((const unsigned*)((const char*)(gbase) + (voff)[_i]), (PG8_LAS unsigned*)(lds + (bufoff) + ldsw + _i * 8192), 16, 0, 0); } while (0)
; #define PG8_WAIT_V(n) asm volatile("s_waitcnt vmcnt(" #n ")" ::: "memory")
; #define PG8_BAR __builtin_amdgcn_s_barrier()
; template <class Epi, class Sched, bool ALIGN_EPI = false, bool SP2 = false>
; __device__ __forceinline__ void gemm_phase(PG8_LAS unsigned char* lds, const Gemm g, const Sched& S, const Epi& E) {
;     ...
;     const int aoff = lds_byte(wr * 64 + fr, fq * 8), boff = lds_byte(wc * 32 + fr, fq * 8);
;     ...
;         PG8_WAIT_V(2); PG8_BAR;
;         PG8_STAGE(PG8_SB(1, 0), cB + kstep, voffB); PG8_STAGE(PG8_SA(1, 0), cA + kstep, voffA); PG8_STAGE(PG8_SB(1, 1), cB + hstep + kstep, voffB);
;         PG8_WAIT_V(6); PG8_BAR;
.LBB0_59:
	v_and_b32_e32 v15, 15, v14
	v_lshrrev_b32_e32 v14, 1, v14
	v_and_b32_e32 v14, 24, v14
	v_lshlrev_b32_e32 v16, 1, v14
	v_lshl_or_b32 v140, s8, 6, v15
	v_lshl_or_b32 v16, v15, 6, v16
	v_lshlrev_b32_e32 v15, 2, v15
	s_sext_i32_i16 s17, s6
	s_lshl_b32 s6, s8, 13
	v_and_b32_e32 v17, 32, v15
	v_bitop3_b32 v18, v16, s6, v17 bitop3:0xde
	s_lshl_b32 s6, s9, 5
	s_add_i32 m0, s34, 0x18000
	v_lshl_add_u64 v[6:7], v[6:7], 0, s[10:11]
	s_and_b32 s9, s6, 0x60
	s_waitcnt vmcnt(2)
	s_barrier
	global_load_lds_dwordx4 v[6:7], off
	v_lshl_add_u64 v[4:5], v[4:5], 0, s[10:11]
	s_add_i32 m0, s34, 0x1a000
	s_add_i32 s38, s34, 0x8000
	s_lshl_b32 s6, s9, 7
	global_load_lds_dwordx4 v[4:5], off
	v_lshl_add_u64 v[0:1], v[0:1], 0, s[10:11]
	s_mov_b32 m0, s38
	s_add_i32 s39, s34, 0xa000
	global_load_lds_dwordx4 v[0:1], off
	v_lshl_add_u64 v[0:1], v[2:3], 0, s[10:11]
	s_add_u32 s10, s20, 0x40080
	s_mov_b32 m0, s39
	s_addc_u32 s11, s21, 0
	global_load_lds_dwordx4 v[0:1], off
	s_add_i32 m0, s34, 0x1c000
	v_lshl_add_u64 v[0:1], s[10:11], 0, v[64:65]
	global_load_lds_dwordx4 v[0:1], off
	v_lshl_add_u64 v[0:1], s[10:11], 0, v[130:131]
	s_add_i32 m0, s34, 0x1e000
	s_cmpk_lt_u32 s7, 0x100
	global_load_lds_dwordx4 v[0:1], off
	v_lshlrev_b32_e32 v0, 14, v12
	v_and_b32_e32 v0, 0xffff8000, v0
	v_lshl_add_u32 v0, v11, 11, v0
	v_and_b32_e32 v1, 1, v12
	v_lshl_or_b32 v0, v1, 6, v0
	v_lshl_add_u32 v136, v13, 1, v0
	v_lshlrev_b32_e32 v0, 14, v8
	v_bitop3_b32 v141, v16, s6, v17 bitop3:0xde
	s_cselect_b64 s[6:7], -1, 0
	s_lshl_b32 s8, s8, 8
	v_and_b32_e32 v0, 0xffff8000, v0
	s_waitcnt vmcnt(6)
	s_add_i32 s8, s8, 0
	v_lshl_add_u32 v0, v9, 11, v0
	v_and_b32_e32 v1, 1, v8
	s_add_i32 s8, s8, 0x20000
	v_lshl_or_b32 v0, v1, 6, v0
	v_add_u32_e32 v142, s8, v15
	v_or_b32_e32 v143, s9, v14
	v_mov_b32_e32 v137, v65
	v_lshl_add_u32 v138, v10, 1, v0
	v_mov_b32_e32 v139, v65
	s_mov_b32 s44, 0
	v_add_u32_e32 v144, 0, v18
	s_mov_b32 s40, 0
	s_barrier
	s_nop 0
	s_branch .LBB0_62

; #define PG8_STAGE(bufoff, gbase, voff) do { _Pragma("unroll") for (int _i = 0; _i < 2; ++_i) \
;         __builtin_amdgcn_global_load_lds((const unsigned*)((const char*)(gbase) + (voff)[_i]), (PG8_LAS unsigned*)(lds + (bufoff) + ldsw + _i * 8192), 16, 0, 0); } while (0)
; #define PG8_LDA(dst, b, h) do { _Pragma("unroll") for (int m = 0; m < 4; ++m) _Pragma("unroll") for (int k = 0; k < 2; ++k) dst[m][k] = *(const PG8_LAS bf16x8*)(lds + PG8_SA(b, h) + aoff + m * 2048 + k * 1024); } while (0)
; #define PG8_LDB(dst, b, h) do { _Pragma("unroll") for (int n = 0; n < 2; ++n) _Pragma("unroll") for (int k = 0; k < 2; ++k) dst[n][k] = *(const PG8_LAS bf16x8*)(lds + PG8_SB(b, h) + boff + n * 2048 + k * 1024); } while (0)
; #define PG8_WAIT_V(n) asm volatile("s_waitcnt vmcnt(" #n ")" ::: "memory")
; #define PG8_WAIT_L(n) asm volatile("s_waitcnt lgkmcnt(" #n ")" ::: "memory")
; #define PG8_BAR __builtin_amdgcn_s_barrier()
; #define PG8_SCHED __builtin_amdgcn_sched_barrier(0)
; template <class Epi, class Sched, bool ALIGN_EPI = false, bool SP2 = false>
; __device__ __forceinline__ void gemm_phase(PG8_LAS unsigned char* lds, const Gemm g, const Sched& S, const Epi& E) {
;     ...
;         const bool has_next = S.next(ui + 1, nxt);
;         const char* nA = has_next ? (const char*)g.A + (size_t)nxt.pm * tstep : cA; const char* nB = has_next ? (const char*)g.Bt + (size_t)nxt.pn * tstep : cB;
;         for (int t = 0; t < nt; t += 2) {
;             const bool last = (t == nt - 2);
;             const char* a1 = cA + (size_t)(t + 1) * kstep;
;             const char* a2 = last ? nA : cA + (size_t)(t + 2) * kstep; const char* b2 = last ? nB : cB + (size_t)(t + 2) * kstep;
;             const char* a3 = a2 + kstep; const char* b3 = b2 + kstep;
;             if (last && has_next) S.a_ready(nxt);
;             if constexpr (SP2) {
;             PG8_LDB(B0, 0, 0); PG8_LDB(B1, 0, 1); PG8_SCHED; PG8_LDA(At, 0, 0); PG8_STAGE(PG8_SA(1, 1), a1 + hstep, voffA);
;             PG8_WAIT_V(8); PG8_WAIT_L(0); PG8_BAR; PG8_MMA(0, 0, At, B0); PG8_MMA(0, 1, At, B1); PG8_BAR; PG8_SCHED;
;             PG8_LDA(At, 0, 1); PG8_STAGE(PG8_SB(0, 0), b2, voffB); PG8_STAGE(PG8_SB(0, 1), b2 + hstep, voffB); PG8_STAGE(PG8_SA(0, 0), a2, voffA);
;             PG8_WAIT_V(8); PG8_WAIT_L(0); PG8_BAR; PG8_MMA(1, 0, At, B0); PG8_MMA(1, 1, At, B1); PG8_BAR; PG8_SCHED;
.LBB0_96:
	s_add_u32 s18, s18, 0x80
	s_addc_u32 s19, s19, 0
	s_add_u32 s22, s22, 0x100
	s_addc_u32 s23, s23, 0
	s_mov_b32 s20, 0
	s_nop 0
	s_mov_b64 s[56:57], 0x80
	s_add_i32 s46, s20, 2
	s_add_u32 s47, s18, 0x80
	s_addc_u32 s21, s19, 0
	s_add_i32 s54, 0, 0x10000
	s_cmp_eq_u32 s41, s20
	s_cselect_b32 s21, s1, s21
	s_cselect_b32 s20, s0, s47
	v_add_u32_e32 v64, s54, v231
	s_cselect_b32 s53, s17, s23
	s_cselect_b32 s52, s16, s22
	s_add_i32 s47, 0, 0x14000
	ds_read_b128 v[56:59], v64
	ds_read_b128 v[72:75], v64 offset:1024
	ds_read_b128 v[76:79], v64 offset:2048
	ds_read_b128 v[80:83], v64 offset:3072
	v_add_u32_e32 v64, s47, v231
	ds_read_b128 v[84:87], v64
	ds_read_b128 v[88:91], v64 offset:1024
	ds_read_b128 v[92:95], v64 offset:2048
	ds_read_b128 v[100:103], v64 offset:3072
	v_lshl_add_u64 v[66:67], s[18:19], 0, v[196:197]
	s_add_i32 m0, s33, 0xc000
	ds_read_b128 v[116:119], v233
	ds_read_b128 v[120:123], v233 offset:1024
	ds_read_b128 v[140:143], v233 offset:2048
	ds_read_b128 v[144:147], v233 offset:3072
	ds_read_b128 v[180:183], v233 offset:4096
	ds_read_b128 v[200:203], v233 offset:5120
	ds_read_b128 v[204:207], v233 offset:6144
	ds_read_b128 v[208:211], v233 offset:7168
	global_load_lds_dwordx4 v[66:67], off
	v_lshl_add_u64 v[66:67], s[18:19], 0, v[198:199]
	s_add_i32 m0, s33, 0xe000
	s_nop 0
	global_load_lds_dwordx4 v[66:67], off
	s_waitcnt vmcnt(8)
	s_waitcnt lgkmcnt(0)
	s_barrier
	v_mfma_f32_16x16x32_bf16 v[176:179], v[56:59], v[116:119], 0
	v_mfma_f32_16x16x32_bf16 v[172:175], v[76:79], v[116:119], 0
	v_mfma_f32_16x16x32_bf16 v[160:163], v[56:59], v[140:143], 0
	v_mfma_f32_16x16x32_bf16 v[156:159], v[76:79], v[140:143], 0
	v_mfma_f32_16x16x32_bf16 v[136:139], v[56:59], v[180:183], 0
	v_mfma_f32_16x16x32_bf16 v[132:135], v[76:79], v[180:183], 0
	v_mfma_f32_16x16x32_bf16 v[112:115], v[56:59], v[204:207], 0
	v_mfma_f32_16x16x32_bf16 v[108:111], v[76:79], v[204:207], 0
	v_mfma_f32_16x16x32_bf16 v[176:179], v[72:75], v[120:123], v[176:179]
	v_mfma_f32_16x16x32_bf16 v[172:175], v[80:83], v[120:123], v[172:175]
	v_mfma_f32_16x16x32_bf16 v[160:163], v[72:75], v[144:147], v[160:163]
	v_mfma_f32_16x16x32_bf16 v[156:159], v[80:83], v[144:147], v[156:159]
	v_mfma_f32_16x16x32_bf16 v[136:139], v[72:75], v[200:203], v[136:139]
	v_mfma_f32_16x16x32_bf16 v[132:135], v[80:83], v[200:203], v[132:135]
	v_mfma_f32_16x16x32_bf16 v[112:115], v[72:75], v[208:211], v[112:115]
	v_mfma_f32_16x16x32_bf16 v[108:111], v[80:83], v[208:211], v[108:111]
	v_mfma_f32_16x16x32_bf16 v[168:171], v[84:87], v[116:119], 0
	v_mfma_f32_16x16x32_bf16 v[116:119], v[92:95], v[116:119], 0
	v_mfma_f32_16x16x32_bf16 v[128:131], v[84:87], v[180:183], 0
	v_mfma_f32_16x16x32_bf16 v[124:127], v[92:95], v[180:183], 0
	v_mfma_f32_16x16x32_bf16 v[104:107], v[84:87], v[204:207], 0
	v_mfma_f32_16x16x32_bf16 v[96:99], v[92:95], v[204:207], 0
	v_mfma_f32_16x16x32_bf16 v[168:171], v[88:91], v[120:123], v[168:171]
	v_mfma_f32_16x16x32_bf16 v[116:119], v[100:103], v[120:123], v[116:119]
	v_mfma_f32_16x16x32_bf16 v[120:123], v[84:87], v[140:143], 0
	v_mfma_f32_16x16x32_bf16 v[140:143], v[92:95], v[140:143], 0
	v_mfma_f32_16x16x32_bf16 v[128:131], v[88:91], v[200:203], v[128:131]
	v_mfma_f32_16x16x32_bf16 v[124:127], v[100:103], v[200:203], v[124:127]
	v_mfma_f32_16x16x32_bf16 v[104:107], v[88:91], v[208:211], v[104:107]
	v_mfma_f32_16x16x32_bf16 v[96:99], v[100:103], v[208:211], v[96:99]
	v_mfma_f32_16x16x32_bf16 v[120:123], v[88:91], v[144:147], v[120:123]
	v_mfma_f32_16x16x32_bf16 v[140:143], v[100:103], v[144:147], v[140:143]
	s_barrier
	s_add_i32 s54, s54, s27
	v_lshl_add_u64 v[234:235], s[52:53], 0, v[190:191]
	s_mov_b32 m0, s54
	ds_read_b128 v[144:147], v233 offset:16384
	ds_read_b128 v[148:151], v233 offset:17408
	ds_read_b128 v[152:155], v233 offset:18432
	ds_read_b128 v[164:167], v233 offset:19456
	ds_read_b128 v[180:183], v233 offset:20480
	ds_read_b128 v[200:203], v233 offset:21504
	ds_read_b128 v[204:207], v233 offset:22528
	ds_read_b128 v[208:211], v233 offset:23552
	global_load_lds_dwordx4 v[234:235], off
	s_add_i32 m0, s54, 0x2000
	v_lshl_add_u64 v[236:237], s[52:53], 0, v[194:195]
	s_add_u32 s52, s52, s2
	s_addc_u32 s53, s53, 0
	s_add_i32 s47, s47, s27
	global_load_lds_dwordx4 v[236:237], off
	v_lshl_add_u64 v[238:239], s[52:53], 0, v[190:191]
	s_mov_b32 m0, s47
	v_lshl_add_u64 v[240:241], s[52:53], 0, v[194:195]
	global_load_lds_dwordx4 v[238:239], off
	s_add_i32 m0, s47, 0x2000
	v_lshl_add_u64 v[242:243], s[20:21], 0, v[188:189]
	global_load_lds_dwordx4 v[240:241], off
	s_mov_b32 m0, s33
	v_lshl_add_u64 v[244:245], s[20:21], 0, v[192:193]
	global_load_lds_dwordx4 v[242:243], off
	s_mov_b32 m0, s34
	s_nop 0
	global_load_lds_dwordx4 v[244:245], off
	s_waitcnt vmcnt(8)
	s_waitcnt lgkmcnt(0)
	s_barrier
; #define PG8_STAGE(bufoff, gbase, voff) do { _Pragma("unroll") for (int _i = 0; _i < 2; ++_i) \
;         __builtin_amdgcn_global_load_lds((const unsigned*)((const char*)(gbase) + (voff)[_i]), (PG8_LAS unsigned*)(lds + (bufoff) + ldsw + _i * 8192), 16, 0, 0); } while (0)
; #define PG8_LDA(dst, b, h) do { _Pragma("unroll") for (int m = 0; m < 4; ++m) _Pragma("unroll") for (int k = 0; k < 2; ++k) dst[m][k] = *(const PG8_LAS bf16x8*)(lds + PG8_SA(b, h) + aoff + m * 2048 + k * 1024); } while (0)
; #define PG8_LDB(dst, b, h) do { _Pragma("unroll") for (int n = 0; n < 2; ++n) _Pragma("unroll") for (int k = 0; k < 2; ++k) dst[n][k] = *(const PG8_LAS bf16x8*)(lds + PG8_SB(b, h) + boff + n * 2048 + k * 1024); } while (0)
; #define PG8_MMA(ai, bj, At, Bt) do { __builtin_amdgcn_s_setprio(1); _Pragma("unroll") for (int m = 0; m < 4; ++m) _Pragma("unroll") for (int n = 0; n < 2; ++n) _Pragma("unroll") for (int k = 0; k < 2; ++k) \
;         acc[ai][bj][m][n] = __builtin_amdgcn_mfma_f32_16x16x32_bf16(Bt[n][k], At[m][k], acc[ai][bj][m][n], 0, 0, 0); __builtin_amdgcn_s_setprio(0); } while (0)
; #define PG8_WAIT_V(n) asm volatile("s_waitcnt vmcnt(" #n ")" ::: "memory")
; #define PG8_WAIT_L(n) asm volatile("s_waitcnt lgkmcnt(" #n ")" ::: "memory")
; #define PG8_BAR __builtin_amdgcn_s_barrier()
; #define PG8_SCHED __builtin_amdgcn_sched_barrier(0)
; template <class Epi, class Sched, bool ALIGN_EPI = false, bool SP2 = false>
; __device__ __forceinline__ void gemm_phase(PG8_LAS unsigned char* lds, const Gemm g, const Sched& S, const Epi& E) {
;     ...
;             PG8_WAIT_V(8); PG8_WAIT_L(0); PG8_BAR; PG8_MMA(1, 0, At, B0); PG8_MMA(1, 1, At, B1); PG8_BAR; PG8_SCHED;
;             PG8_LDB(B0, 1, 0); PG8_LDB(B1, 1, 1); PG8_SCHED; PG8_LDA(At, 1, 0); PG8_STAGE(PG8_SA(0, 1), a2 + hstep, voffA);
;             PG8_WAIT_V(8); PG8_WAIT_L(0); PG8_BAR; PG8_MMA(0, 0, At, B0); PG8_MMA(0, 1, At, B1); PG8_BAR; PG8_SCHED;
	v_mfma_f32_16x16x32_bf16 v[66:69], v[56:59], v[144:147], 0
	v_mfma_f32_16x16x32_bf16 v[60:63], v[76:79], v[144:147], 0
	v_mfma_f32_16x16x32_bf16 v[44:47], v[56:59], v[152:155], 0
	v_mfma_f32_16x16x32_bf16 v[40:43], v[76:79], v[152:155], 0
	v_mfma_f32_16x16x32_bf16 v[28:31], v[56:59], v[180:183], 0
	v_mfma_f32_16x16x32_bf16 v[24:27], v[76:79], v[180:183], 0
	v_mfma_f32_16x16x32_bf16 v[12:15], v[56:59], v[204:207], 0
	v_mfma_f32_16x16x32_bf16 v[8:11], v[76:79], v[204:207], 0
	v_mfma_f32_16x16x32_bf16 v[66:69], v[72:75], v[148:151], v[66:69]
	v_mfma_f32_16x16x32_bf16 v[60:63], v[80:83], v[148:151], v[60:63]
	v_mfma_f32_16x16x32_bf16 v[44:47], v[72:75], v[164:167], v[44:47]
	v_mfma_f32_16x16x32_bf16 v[40:43], v[80:83], v[164:167], v[40:43]
	v_mfma_f32_16x16x32_bf16 v[28:31], v[72:75], v[200:203], v[28:31]
	v_mfma_f32_16x16x32_bf16 v[24:27], v[80:83], v[200:203], v[24:27]
	v_mfma_f32_16x16x32_bf16 v[12:15], v[72:75], v[208:211], v[12:15]
	v_mfma_f32_16x16x32_bf16 v[8:11], v[80:83], v[208:211], v[8:11]
	v_mfma_f32_16x16x32_bf16 v[52:55], v[84:87], v[144:147], 0
	v_mfma_f32_16x16x32_bf16 v[48:51], v[92:95], v[144:147], 0
	v_mfma_f32_16x16x32_bf16 v[36:39], v[84:87], v[152:155], 0
	v_mfma_f32_16x16x32_bf16 v[32:35], v[92:95], v[152:155], 0
	v_mfma_f32_16x16x32_bf16 v[20:23], v[84:87], v[180:183], 0
	v_mfma_f32_16x16x32_bf16 v[16:19], v[92:95], v[180:183], 0
	v_mfma_f32_16x16x32_bf16 v[4:7], v[84:87], v[204:207], 0
	v_mfma_f32_16x16x32_bf16 v[0:3], v[92:95], v[204:207], 0
	v_mfma_f32_16x16x32_bf16 v[52:55], v[88:91], v[148:151], v[52:55]
	v_mfma_f32_16x16x32_bf16 v[48:51], v[100:103], v[148:151], v[48:51]
	v_mfma_f32_16x16x32_bf16 v[36:39], v[88:91], v[164:167], v[36:39]
	v_mfma_f32_16x16x32_bf16 v[32:35], v[100:103], v[164:167], v[32:35]
	v_mfma_f32_16x16x32_bf16 v[20:23], v[88:91], v[200:203], v[20:23]
	v_mfma_f32_16x16x32_bf16 v[16:19], v[100:103], v[200:203], v[16:19]
	v_mfma_f32_16x16x32_bf16 v[4:7], v[88:91], v[208:211], v[4:7]
	v_mfma_f32_16x16x32_bf16 v[0:3], v[100:103], v[208:211], v[0:3]
	s_barrier
	s_add_i32 s47, 0, 0x18000
	v_add_u32_e32 v64, s47, v231
	s_add_i32 s52, 0, 0x1c000
	ds_read_b128 v[56:59], v64
	ds_read_b128 v[72:75], v64 offset:1024
	ds_read_b128 v[76:79], v64 offset:2048
	ds_read_b128 v[80:83], v64 offset:3072
	v_add_u32_e32 v64, s52, v231
	ds_read_b128 v[84:87], v64
	ds_read_b128 v[88:91], v64 offset:1024
	ds_read_b128 v[92:95], v64 offset:2048
	ds_read_b128 v[100:103], v64 offset:3072
	s_add_u32 s20, s20, s2
	s_addc_u32 s21, s21, 0
	s_mov_b32 m0, s35
	v_lshl_add_u64 v[70:71], s[20:21], 0, v[188:189]
	ds_read_b128 v[144:147], v233 offset:32768
	ds_read_b128 v[148:151], v233 offset:33792
	ds_read_b128 v[180:183], v233 offset:34816
	ds_read_b128 v[200:203], v233 offset:35840
	ds_read_b128 v[204:207], v233 offset:36864
	ds_read_b128 v[208:211], v233 offset:37888
	ds_read_b128 v[212:215], v233 offset:38912
	ds_read_b128 v[216:219], v233 offset:39936
	global_load_lds_dwordx4 v[70:71], off
	v_lshl_add_u64 v[70:71], s[20:21], 0, v[192:193]
	s_mov_b32 m0, s36
	s_nop 0
	global_load_lds_dwordx4 v[70:71], off
	s_waitcnt vmcnt(8)
	s_waitcnt lgkmcnt(0)
	s_barrier
	v_mfma_f32_16x16x32_bf16 v[152:155], v[56:59], v[144:147], v[176:179]
	v_mfma_f32_16x16x32_bf16 v[176:179], v[72:75], v[148:151], v[152:155]
	v_mfma_f32_16x16x32_bf16 v[152:155], v[76:79], v[144:147], v[172:175]
	v_mfma_f32_16x16x32_bf16 v[172:175], v[80:83], v[148:151], v[152:155]
	v_mfma_f32_16x16x32_bf16 v[152:155], v[56:59], v[180:183], v[160:163]
	v_mfma_f32_16x16x32_bf16 v[160:163], v[72:75], v[200:203], v[152:155]
	v_mfma_f32_16x16x32_bf16 v[152:155], v[76:79], v[180:183], v[156:159]
	v_mfma_f32_16x16x32_bf16 v[136:139], v[56:59], v[204:207], v[136:139]
	v_mfma_f32_16x16x32_bf16 v[132:135], v[76:79], v[204:207], v[132:135]
	v_mfma_f32_16x16x32_bf16 v[112:115], v[56:59], v[212:215], v[112:115]
	v_mfma_f32_16x16x32_bf16 v[108:111], v[76:79], v[212:215], v[108:111]
	v_mfma_f32_16x16x32_bf16 v[156:159], v[80:83], v[200:203], v[152:155]
	v_mfma_f32_16x16x32_bf16 v[136:139], v[72:75], v[208:211], v[136:139]
	v_mfma_f32_16x16x32_bf16 v[132:135], v[80:83], v[208:211], v[132:135]
	v_mfma_f32_16x16x32_bf16 v[112:115], v[72:75], v[216:219], v[112:115]
	v_mfma_f32_16x16x32_bf16 v[108:111], v[80:83], v[216:219], v[108:111]
	v_mfma_f32_16x16x32_bf16 v[116:119], v[92:95], v[144:147], v[116:119]
	v_mfma_f32_16x16x32_bf16 v[152:155], v[84:87], v[144:147], v[168:171]
	v_mfma_f32_16x16x32_bf16 v[164:167], v[100:103], v[148:151], v[116:119]
	v_mfma_f32_16x16x32_bf16 v[116:119], v[84:87], v[180:183], v[120:123]
	v_mfma_f32_16x16x32_bf16 v[168:171], v[88:91], v[148:151], v[152:155]
	v_mfma_f32_16x16x32_bf16 v[152:155], v[88:91], v[200:203], v[116:119]
	v_mfma_f32_16x16x32_bf16 v[116:119], v[92:95], v[180:183], v[140:143]
	v_mfma_f32_16x16x32_bf16 v[148:151], v[100:103], v[200:203], v[116:119]
	v_mfma_f32_16x16x32_bf16 v[116:119], v[84:87], v[204:207], v[128:131]
	v_mfma_f32_16x16x32_bf16 v[128:131], v[88:91], v[208:211], v[116:119]
	v_mfma_f32_16x16x32_bf16 v[116:119], v[92:95], v[204:207], v[124:127]
	v_mfma_f32_16x16x32_bf16 v[104:107], v[84:87], v[212:215], v[104:107]
	v_mfma_f32_16x16x32_bf16 v[96:99], v[92:95], v[212:215], v[96:99]
	v_mfma_f32_16x16x32_bf16 v[124:127], v[100:103], v[208:211], v[116:119]
	v_mfma_f32_16x16x32_bf16 v[104:107], v[88:91], v[216:219], v[104:107]
	v_mfma_f32_16x16x32_bf16 v[96:99], v[100:103], v[216:219], v[96:99]
	s_barrier
; #define PG8_STAGE(bufoff, gbase, voff) do { _Pragma("unroll") for (int _i = 0; _i < 2; ++_i) \
;         __builtin_amdgcn_global_load_lds((const unsigned*)((const char*)(gbase) + (voff)[_i]), (PG8_LAS unsigned*)(lds + (bufoff) + ldsw + _i * 8192), 16, 0, 0); } while (0)
; #define PG8_LDA(dst, b, h) do { _Pragma("unroll") for (int m = 0; m < 4; ++m) _Pragma("unroll") for (int k = 0; k < 2; ++k) dst[m][k] = *(const PG8_LAS bf16x8*)(lds + PG8_SA(b, h) + aoff + m * 2048 + k * 1024); } while (0)
; #define PG8_MMA(ai, bj, At, Bt) do { __builtin_amdgcn_s_setprio(1); _Pragma("unroll") for (int m = 0; m < 4; ++m) _Pragma("unroll") for (int n = 0; n < 2; ++n) _Pragma("unroll") for (int k = 0; k < 2; ++k) \
;         acc[ai][bj][m][n] = __builtin_amdgcn_mfma_f32_16x16x32_bf16(Bt[n][k], At[m][k], acc[ai][bj][m][n], 0, 0, 0); __builtin_amdgcn_s_setprio(0); } while (0)
; #define PG8_WAIT_V(n) asm volatile("s_waitcnt vmcnt(" #n ")" ::: "memory")
; #define PG8_WAIT_L(n) asm volatile("s_waitcnt lgkmcnt(" #n ")" ::: "memory")
; #define PG8_BAR __builtin_amdgcn_s_barrier()
; #define PG8_SCHED __builtin_amdgcn_sched_barrier(0)
; template <class Epi, class Sched, bool ALIGN_EPI = false, bool SP2 = false>
; __device__ __forceinline__ void gemm_phase(PG8_LAS unsigned char* lds, const Gemm g, const Sched& S, const Epi& E) {
;     ...
;         for (int t = 0; t < nt; t += 2) {
;     ...
;             PG8_LDA(At, 1, 1); PG8_STAGE(PG8_SB(1, 0), b3, voffB); PG8_STAGE(PG8_SB(1, 1), b3 + hstep, voffB); PG8_STAGE(PG8_SA(1, 0), a3, voffA);
;             PG8_WAIT_V(8); PG8_WAIT_L(0); PG8_BAR; PG8_MMA(1, 0, At, B0); PG8_MMA(1, 1, At, B1); PG8_BAR; PG8_SCHED;
	s_add_i32 s20, s47, s27
	v_lshl_add_u64 v[70:71], v[234:235], 0, s[56:57]
	s_mov_b32 m0, s20
	ds_read_b128 v[116:119], v233 offset:49152
	ds_read_b128 v[120:123], v233 offset:50176
	ds_read_b128 v[140:143], v233 offset:51200
	ds_read_b128 v[144:147], v233 offset:52224
	ds_read_b128 v[180:183], v233 offset:53248
	ds_read_b128 v[200:203], v233 offset:54272
	ds_read_b128 v[204:207], v233 offset:55296
	ds_read_b128 v[208:211], v233 offset:56320
	global_load_lds_dwordx4 v[70:71], off
	v_lshl_add_u64 v[70:71], v[236:237], 0, s[56:57]
	s_add_i32 m0, s20, 0x2000
	s_add_i32 s20, s52, s27
	global_load_lds_dwordx4 v[70:71], off
	v_lshl_add_u64 v[70:71], v[238:239], 0, s[56:57]
	s_mov_b32 m0, s20
	s_nop 0
	global_load_lds_dwordx4 v[70:71], off
	v_lshl_add_u64 v[70:71], v[240:241], 0, s[56:57]
	s_add_i32 m0, s20, 0x2000
	s_nop 0
	global_load_lds_dwordx4 v[70:71], off
	v_lshl_add_u64 v[70:71], v[242:243], 0, s[56:57]
	s_mov_b32 m0, s39
	s_nop 0
	global_load_lds_dwordx4 v[70:71], off
	v_lshl_add_u64 v[70:71], v[244:245], 0, s[56:57]
	s_mov_b32 m0, s40
	s_nop 0
	global_load_lds_dwordx4 v[70:71], off
	s_waitcnt vmcnt(8)
	s_waitcnt lgkmcnt(0)
	s_barrier
	v_mfma_f32_16x16x32_bf16 v[66:69], v[56:59], v[116:119], v[66:69]
	v_mfma_f32_16x16x32_bf16 v[60:63], v[76:79], v[116:119], v[60:63]
	v_mfma_f32_16x16x32_bf16 v[44:47], v[56:59], v[140:143], v[44:47]
	v_mfma_f32_16x16x32_bf16 v[40:43], v[76:79], v[140:143], v[40:43]
	v_mfma_f32_16x16x32_bf16 v[28:31], v[56:59], v[180:183], v[28:31]
	v_mfma_f32_16x16x32_bf16 v[24:27], v[76:79], v[180:183], v[24:27]
	v_mfma_f32_16x16x32_bf16 v[12:15], v[56:59], v[204:207], v[12:15]
	v_mfma_f32_16x16x32_bf16 v[8:11], v[76:79], v[204:207], v[8:11]
	v_mfma_f32_16x16x32_bf16 v[68:71], v[72:75], v[120:123], v[66:69]
	v_mfma_f32_16x16x32_bf16 v[60:63], v[80:83], v[120:123], v[60:63]
	v_mfma_f32_16x16x32_bf16 v[44:47], v[72:75], v[144:147], v[44:47]
	v_mfma_f32_16x16x32_bf16 v[40:43], v[80:83], v[144:147], v[40:43]
	v_mfma_f32_16x16x32_bf16 v[28:31], v[72:75], v[200:203], v[28:31]
	v_mfma_f32_16x16x32_bf16 v[24:27], v[80:83], v[200:203], v[24:27]
	v_mfma_f32_16x16x32_bf16 v[12:15], v[72:75], v[208:211], v[12:15]
	v_mfma_f32_16x16x32_bf16 v[8:11], v[80:83], v[208:211], v[8:11]
	v_mfma_f32_16x16x32_bf16 v[52:55], v[84:87], v[116:119], v[52:55]
	v_mfma_f32_16x16x32_bf16 v[48:51], v[92:95], v[116:119], v[48:51]
	v_mfma_f32_16x16x32_bf16 v[36:39], v[84:87], v[140:143], v[36:39]
	v_mfma_f32_16x16x32_bf16 v[32:35], v[92:95], v[140:143], v[32:35]
	v_mfma_f32_16x16x32_bf16 v[20:23], v[84:87], v[180:183], v[20:23]
	v_mfma_f32_16x16x32_bf16 v[16:19], v[92:95], v[180:183], v[16:19]
	v_mfma_f32_16x16x32_bf16 v[4:7], v[84:87], v[204:207], v[4:7]
	v_mfma_f32_16x16x32_bf16 v[0:3], v[92:95], v[204:207], v[0:3]
	v_mfma_f32_16x16x32_bf16 v[52:55], v[88:91], v[120:123], v[52:55]
	v_mfma_f32_16x16x32_bf16 v[48:51], v[100:103], v[120:123], v[48:51]
	v_mfma_f32_16x16x32_bf16 v[36:39], v[88:91], v[144:147], v[36:39]
	v_mfma_f32_16x16x32_bf16 v[32:35], v[100:103], v[144:147], v[32:35]
	v_mfma_f32_16x16x32_bf16 v[20:23], v[88:91], v[200:203], v[20:23]
	v_mfma_f32_16x16x32_bf16 v[16:19], v[100:103], v[200:203], v[16:19]
	v_mfma_f32_16x16x32_bf16 v[4:7], v[88:91], v[208:211], v[4:7]
	v_mfma_f32_16x16x32_bf16 v[0:3], v[100:103], v[208:211], v[0:3]
	s_barrier
	s_add_u32 s18, s18, 0x100
	s_addc_u32 s19, s19, 0
	s_add_u32 s22, s22, 0x100
	s_addc_u32 s23, s23, 0
	s_cmp_ge_u32 s46, s38
	s_mov_b32 s20, s46
